# deferred layer-1 FFN weight conversion in the HGRN2 phase: down-proj weights converted only by the 128 workgroups without a prompt unit, gate weights by all 256 (25/75 split instead of 50/50)
# baseline (speedup 1.0000x reference)
.LBB0_3561:
	s_mov_b64 s[14:15], 0
	v_readlane_b32 s6, v255, 9
	s_and_b64 s[4:5], s[34:35], s[14:15]
	v_readlane_b32 s7, v255, 10
	s_add_i32 s3, s6, 0xfffffc00
	s_mov_b32 s8, s6
	s_and_b64 s[6:7], s[14:15], exec
	s_cselect_b32 s3, s3, s8
	s_cmpk_gt_i32 s3, 0x2aff
	s_cselect_b64 s[6:7], -1, 0
	s_or_b64 s[4:5], s[4:5], s[6:7]
	s_and_b64 vcc, exec, s[4:5]
	s_cbranch_vccnz .LBB0_3566
	s_lshl_b32 s4, s91, 14
	s_add_i32 s6, s4, 0
	v_lshlrev_b32_e32 v2, 2, v0
	s_and_b64 s[4:5], s[14:15], exec
	v_and_b32_e32 v16, 60, v2
	v_and_b32_e32 v2, 0x60, v116
	v_readlane_b32 s4, v255, 11
	v_add_u32_e32 v5, s6, v2
	v_lshlrev_b32_e32 v2, 4, v31
	v_readlane_b32 s5, v255, 12
	v_mov_b32_e32 v3, 0
	v_add_u32_e32 v17, s6, v2
	v_mul_u32_u24_e32 v18, 0x88, v29
	s_cselect_b32 s8, 0x400, s4
	v_mul_u32_u24_e32 v15, 0x88, v16
	v_lshl_add_u64 v[6:7], s[38:39], 0, v[2:3]
	s_mov_b64 s[4:5], 0x2c200000
	s_lshl_b32 s9, s3, 6
	v_lshlrev_b32_e32 v2, 2, v16
	v_add_u32_e32 v16, v17, v18
	v_lshlrev_b32_e32 v4, 3, v31
	v_lshl_add_u64 v[6:7], v[6:7], 0, s[4:5]
	v_or_b32_e32 v8, 8, v29
	v_or_b32_e32 v9, 16, v29
	v_or_b32_e32 v10, 24, v29
	v_or_b32_e32 v11, 32, v29
	v_or_b32_e32 v12, 40, v29
	v_or_b32_e32 v13, 48, v29
	v_or_b32_e32 v14, 56, v29
	s_lshl_b32 s10, s8, 6
	s_mov_b32 s11, 0xac00000
	s_mov_b32 s12, 0xac04000
	s_mov_b32 s13, 0xac08000
	s_mov_b32 s14, 0xac0c000
	s_mov_b32 s15, 0xac10000
	s_mov_b32 s16, 0xac14000
	s_mov_b32 s17, 0xac18000
	s_mov_b32 s18, 0xac1c000
	s_mov_b32 s19, 0xac20000
	s_mov_b32 s20, 0xac24000
	s_mov_b32 s21, 0xac28000
	s_mov_b32 s22, 0xac2c000
	s_mov_b32 s23, 0xac30000
	s_mov_b32 s24, 0xac34000
	s_mov_b32 s25, 0xac38000
	s_mov_b32 s26, 0xac3c000
	v_add_u32_e32 v15, v5, v15
	s_movk_i32 s27, 0x5600
	v_add_u32_e32 v5, 0x880, v16
	v_add_u32_e32 v17, 0xcc0, v16
	v_add_u32_e32 v18, 0x1100, v16
	v_add_u32_e32 v19, 0x1540, v16
	v_add_u32_e32 v20, 0x1980, v16
	v_add_u32_e32 v21, 0x1dc0, v16
	s_cmpk_eq_i32 s44, 0x100
	s_cbranch_scc0 .Lb2_noskew
	s_and_b64 vcc, exec, s[34:35]
	s_cbranch_vccnz .Lb2_skipD
	v_readlane_b32 s3, v255, 9
	s_nop 3
	s_add_i32 s3, s3, 0xfffffc00
	s_movk_i32 s8, 0x400
	s_lshl_b32 s9, s3, 6
	s_lshl_b32 s10, s8, 6
.Lb2_noskew:
	s_mov_b32 s28, s9
	s_mov_b32 s29, s3

.Lb2_skipD:
	v_readlane_b32 s3, v255, 9
	v_readlane_b32 s8, v255, 11
	s_nop 3
	s_lshl_b32 s9, s3, 6
	s_lshl_b32 s10, s8, 6
	v_mov_b32_e32 v3, 0
	v_lshlrev_b32_e32 v4, 1, v4
	v_mov_b32_e32 v5, v3
	v_lshl_add_u64 v[4:5], s[38:39], 0, v[4:5]
	s_mov_b64 s[4:5], 0x21600000
	v_lshl_add_u64 v[4:5], v[4:5], 0, s[4:5]
	s_mul_i32 s4, s3, 0xac000
	v_bfe_u32 v6, v0, 4, 2
	s_mov_b32 s5, 0x2b000
	v_mov_b32_e32 v7, s4
	v_mad_u32_u24 v6, v6, s5, v7
	s_mul_i32 s6, s8, 0xac000
	s_mov_b32 s7, 0xac00000
	s_mov_b32 s11, 0xac0a000
	s_mov_b32 s12, 0xac15000
	s_mov_b32 s13, 0xac20000
	s_mov_b32 s14, 0xac2b000
	s_mov_b32 s15, 0xac35000
	s_mov_b32 s16, 0xac40000
	s_mov_b32 s17, 0xac4b000
	s_mov_b32 s18, 0xac56000
	s_mov_b32 s19, 0xac60000
	s_mov_b32 s20, 0xac6b000
	s_mov_b32 s21, 0xac76000
	s_mov_b32 s22, 0xac81000
	s_mov_b32 s23, 0xac8b000
	s_mov_b32 s24, 0xac96000
	s_mov_b32 s25, 0xaca1000
